# v70 + software L2 prefetch of the next unit's inputs in the GLA chunk phases G1 and G3 (dummy dword loads issued late in each unit)
# baseline (speedup 1.0000x reference)
.LBB0_606:
	s_or_b64 exec, exec, s[38:39]
	v_readlane_b32 s4, v251, 27
	s_waitcnt lgkmcnt(0)
	v_mov_b32_e32 v0, v222
	v_readlane_b32 s5, v251, 28
	s_barrier
	s_and_b64 vcc, exec, s[4:5]
	v_readfirstlane_b32 s2, v0
	s_cbranch_vccz .LBB0_642
	v_ashrrev_i32_e32 v1, 2, v0
	v_subrev_u32_e32 v64, 64, v1
	v_add_u32_e32 v2, 0x7fd0, v1
	v_cmp_lt_i32_e32 vcc, 47, v1
	v_lshlrev_b32_e32 v1, 2, v0
	v_and_b32_e32 v7, 12, v1
	v_readlane_b32 s4, v251, 7
	v_cndmask_b32_e32 v65, -1, v2, vcc
	v_lshlrev_b32_e32 v142, 2, v7
	v_readlane_b32 s5, v251, 8
	v_lshlrev_b32_e32 v2, 3, v0
	v_and_b32_e32 v8, 0x78, v2
	v_lshl_add_u64 v[28:29], s[4:5], 0, v[142:143]
	v_readlane_b32 s4, v251, 11
	v_lshlrev_b32_e32 v2, 1, v8
	v_mov_b32_e32 v3, v143
	v_readlane_b32 s5, v251, 12
	s_movk_i32 s20, 0x100
	v_mov_b32_e32 v5, v143
	v_lshl_add_u64 v[30:31], s[4:5], 0, v[2:3]
	v_lshlrev_b32_e32 v3, 4, v0
	v_and_b32_e32 v4, 0x1f0, v3
	v_and_b32_e32 v3, 0xffffffc0, v3
	v_add3_u32 v68, 0, v3, v142
	v_ashrrev_i32_e32 v3, 7, v0
	v_lshlrev_b32_e32 v9, 4, v3
	v_or_b32_e32 v13, 2, v9
	v_lshlrev_b32_e32 v14, 6, v13
	v_cmp_gt_i32_e64 s[46:47], 48, v13
	v_or_b32_e32 v13, 3, v9
	v_lshlrev_b32_e32 v15, 6, v13
	v_cmp_gt_i32_e64 s[48:49], 48, v13
	v_or_b32_e32 v13, 4, v9
	v_lshlrev_b32_e32 v16, 6, v13
	v_cmp_gt_i32_e64 s[50:51], 48, v13
	v_or_b32_e32 v13, 5, v9
	v_lshlrev_b32_e32 v17, 6, v13
	v_cmp_gt_i32_e64 s[52:53], 48, v13
	v_or_b32_e32 v13, 6, v9
	v_lshlrev_b32_e32 v18, 6, v13
	v_cmp_gt_i32_e64 s[54:55], 48, v13
	v_or_b32_e32 v13, 7, v9
	v_lshlrev_b32_e32 v19, 6, v13
	v_cmp_gt_i32_e64 s[56:57], 48, v13
	v_or_b32_e32 v13, 8, v9
	v_readlane_b32 s4, v251, 13
	v_lshlrev_b32_e32 v20, 6, v13
	v_cmp_gt_i32_e64 s[58:59], 48, v13
	v_or_b32_e32 v13, 9, v9
	v_readlane_b32 s5, v251, 14
	v_lshlrev_b32_e32 v21, 6, v13
	v_cmp_gt_i32_e64 s[60:61], 48, v13
	v_or_b32_e32 v13, 10, v9
	v_cmp_gt_i32_e64 s[34:35], s20, v0
	s_movk_i32 s20, 0xff
	v_lshl_add_u64 v[32:33], s[4:5], 0, v[4:5]
	v_lshlrev_b32_e32 v22, 6, v13
	v_cmp_gt_i32_e64 s[62:63], 48, v13
	v_or_b32_e32 v13, 11, v9
	v_lshl_add_u32 v72, v8, 2, 0
	v_readlane_b32 s4, v251, 29
	v_cmp_lt_i32_e64 s[40:41], s20, v0
	v_ashrrev_i32_e32 v67, 4, v0
	v_lshlrev_b32_e32 v23, 6, v13
	v_cmp_gt_i32_e64 s[64:65], 48, v13
	v_or_b32_e32 v13, 12, v9
	v_add_u32_e32 v69, 0, v1
	s_movk_i32 s20, 0x2100
	v_sub_u32_e32 v62, v72, v2
	v_ashrrev_i32_e32 v1, 31, v0
	v_readlane_b32 s5, v251, 30
	v_lshrrev_b32_e32 v2, 1, v0
	v_lshlrev_b32_e32 v10, 10, v3
	v_cmp_gt_i32_e64 s[42:43], 3, v3
	v_lshlrev_b32_e32 v24, 6, v13
	v_cmp_gt_i32_e64 s[66:67], 48, v13
	v_or_b32_e32 v13, 13, v9
	v_cmp_lt_i32_e64 s[74:75], 0, v3
	v_cmp_lt_i32_e64 s[76:77], 1, v3
	v_cmp_lt_i32_e64 s[78:79], 2, v3
	v_mul_lo_u32 v27, v3, s20
	v_lshl_add_u64 v[34:35], v[0:1], 2, s[4:5]
	v_and_b32_e32 v2, 24, v2
	v_bfe_u32 v3, v0, 2, 2
	s_ashr_i32 s2, s2, 1
	v_lshlrev_b64 v[36:37], 4, v[0:1]
	v_add_u32_e32 v1, 0x7fd0, v67
	v_cmp_lt_i32_e32 vcc, 47, v67
	v_and_b32_e32 v6, 15, v0
	v_or_b32_e32 v11, 1, v9
	v_lshlrev_b32_e32 v25, 6, v13
	v_cmp_gt_i32_e64 s[68:69], 48, v13
	v_or_b32_e32 v13, 14, v9
	v_or_b32_e32 v9, 15, v9
	v_or_b32_e32 v3, v2, v3
	s_andn2_b32 s2, s2, 31
	v_add_u32_e32 v63, 0, v2
	v_cndmask_b32_e32 v74, -1, v1, vcc
	v_add_u32_e32 v1, 0x7ff0, v67
	v_cmp_lt_i32_e32 vcc, 15, v67
	v_ashrrev_i32_e32 v76, 5, v0
	v_add_u32_e32 v2, 0x200, v0
	v_lshlrev_b32_e32 v26, 6, v13
	v_cmp_gt_i32_e64 s[70:71], 48, v13
	v_lshlrev_b32_e32 v13, 6, v9
	v_cmp_gt_i32_e64 s[72:73], 48, v9
	v_or_b32_e32 v9, s2, v6
	v_cndmask_b32_e32 v75, -1, v1, vcc
	v_add_u32_e32 v1, 0x7fd0, v76
	v_cmp_lt_i32_e32 vcc, 47, v76
	v_ashrrev_i32_e32 v78, 5, v2
	v_add_u32_e32 v6, 0x400, v0
	v_cndmask_b32_e32 v77, -1, v1, vcc
	v_add_u32_e32 v1, 0x7fd0, v78
	v_cmp_lt_i32_e32 vcc, 47, v78
	v_ashrrev_i32_e32 v80, 5, v6
	v_add_u32_e32 v8, 0x600, v0
	v_cndmask_b32_e32 v79, -1, v1, vcc
	v_add_u32_e32 v1, 0x7fd0, v80
	v_cmp_lt_i32_e32 vcc, 47, v80
	v_ashrrev_i32_e32 v82, 5, v8
	v_readlane_b32 s4, v250, 43
	v_cndmask_b32_e32 v81, -1, v1, vcc
	v_add_u32_e32 v1, 0x7fd0, v82
	v_cmp_lt_i32_e32 vcc, 47, v82
	s_movk_i32 s6, 0x210
	v_lshlrev_b32_e32 v7, 1, v7
	v_cndmask_b32_e32 v83, -1, v1, vcc
	v_mov_b32_e32 v1, s4
	v_mad_u32_u24 v46, v3, s6, v1
	s_lshl_b32 s2, s2, 1
	v_add3_u32 v88, v46, v7, s2
	v_mul_u32_u24_e32 v46, 0x110, v3
	v_or_b32_e32 v3, 32, v3
	v_mad_u32_u24 v1, v3, s6, v1
	v_add3_u32 v108, v1, v7, s2
	v_mul_u32_u24_e32 v1, 0x110, v3
	v_add3_u32 v1, 0, v1, v7
	s_movk_i32 s5, 0x110
	v_add3_u32 v46, 0, v46, v7
	v_add_u32_e32 v112, 0xa400, v1
	v_add_u32_e32 v113, 0xa840, v1
	v_add_u32_e32 v114, 0xa420, v1
	v_add_u32_e32 v115, 0xa860, v1
	v_add_u32_e32 v116, 0xa440, v1
	v_add_u32_e32 v117, 0xa880, v1
	v_add_u32_e32 v118, 0xa460, v1
	v_add_u32_e32 v119, 0xa8a0, v1
	v_add_u32_e32 v120, 0xa480, v1
	v_add_u32_e32 v121, 0xa8c0, v1
	v_add_u32_e32 v122, 0xa4a0, v1
	v_add_u32_e32 v123, 0xa8e0, v1
	v_add_u32_e32 v124, 0xa4c0, v1
	v_add_u32_e32 v125, 0xa900, v1
	v_add_u32_e32 v126, 0xa4e0, v1
	v_add_u32_e32 v127, 0xa920, v1
	v_lshrrev_b32_e32 v1, 4, v2
	v_ashrrev_i32_e32 v3, 31, v2
	v_add_u32_e32 v92, 0xa400, v46
	v_add_u32_e32 v93, 0xa840, v46
	v_add_u32_e32 v94, 0xa420, v46
	v_add_u32_e32 v95, 0xa860, v46
	v_add_u32_e32 v96, 0xa440, v46
	v_add_u32_e32 v97, 0xa880, v46
	v_add_u32_e32 v98, 0xa460, v46
	v_add_u32_e32 v99, 0xa8a0, v46
	v_add_u32_e32 v100, 0xa480, v46
	v_add_u32_e32 v101, 0xa8c0, v46
	v_add_u32_e32 v102, 0xa4a0, v46
	v_add_u32_e32 v103, 0xa8e0, v46
	v_add_u32_e32 v104, 0xa4c0, v46
	v_add_u32_e32 v105, 0xa900, v46
	v_add_u32_e32 v106, 0xa4e0, v46
	v_add_u32_e32 v107, 0xa920, v46
	v_lshlrev_b64 v[46:47], 4, v[2:3]
	v_mul_lo_u32 v162, v1, s5
	v_lshrrev_b32_e32 v1, 4, v6
	v_ashrrev_i32_e32 v7, 31, v6
	v_add_u32_e32 v2, 0x800, v0
	v_lshlrev_b64 v[48:49], 4, v[6:7]
	v_mul_lo_u32 v6, v1, s5
	v_lshrrev_b32_e32 v1, 4, v8
	v_ashrrev_i32_e32 v3, 31, v2
	v_mul_lo_u32 v7, v1, s5
	v_lshrrev_b32_e32 v1, 4, v2
	v_lshlrev_b64 v[52:53], 4, v[2:3]
	v_add_u32_e32 v2, 0xa00, v0
	v_mul_lo_u32 v161, v9, s5
	v_ashrrev_i32_e32 v9, 31, v8
	v_ashrrev_i32_e32 v3, 31, v2
	s_movk_i32 s20, 0x80
	v_lshlrev_b64 v[50:51], 4, v[8:9]
	v_mul_lo_u32 v8, v1, s5
	v_lshrrev_b32_e32 v1, 4, v2
	v_lshlrev_b64 v[54:55], 4, v[2:3]
	v_add_u32_e32 v2, 0xc00, v0
	v_and_b32_e32 v66, 0x7f, v0
	v_cmp_gt_i32_e64 s[80:81], s20, v0
	v_mul_lo_u32 v9, v1, s5
	v_lshrrev_b32_e32 v1, 4, v2
	v_ashrrev_i32_e32 v3, 31, v2
	v_add_u32_e32 v0, 0xe00, v0
	v_lshlrev_b64 v[56:57], 4, v[2:3]
	v_mul_lo_u32 v2, v1, s5
	v_lshrrev_b32_e32 v3, 4, v0
	v_ashrrev_i32_e32 v1, 31, v0
	v_lshlrev_b32_e32 v12, 6, v11
	v_cmp_gt_i32_e64 s[44:45], 48, v11
	v_lshl_add_u32 v70, v66, 2, 0
	v_mul_lo_u32 v11, v11, s6
	v_lshlrev_b32_e32 v38, 7, v76
	v_lshlrev_b32_e32 v40, 7, v78
	v_lshlrev_b32_e32 v42, 7, v80
	v_lshlrev_b32_e32 v44, 7, v82
	v_mul_lo_u32 v142, v67, s6
	v_mul_lo_u32 v169, v67, s5
	v_lshlrev_b64 v[58:59], 4, v[0:1]
	v_mul_lo_u32 v0, v3, s5
	v_add_u32_e32 v71, 0, v4
	v_add_u32_e32 v73, s4, v4
	v_ashrrev_i32_e32 v39, 31, v38
	v_mul_lo_u32 v84, v76, s6
	v_ashrrev_i32_e32 v41, 31, v40
	v_mul_lo_u32 v85, v78, s6
	v_ashrrev_i32_e32 v43, 31, v42
	v_mul_lo_u32 v86, v80, s6
	v_ashrrev_i32_e32 v45, 31, v44
	v_mul_lo_u32 v87, v82, s6
	v_add_u32_e32 v89, 0x840, v88
	v_add_u32_e32 v90, 32, v88
	v_add_u32_e32 v91, 0x860, v88
	v_add_u32_e32 v109, 0x840, v108
	v_add_u32_e32 v110, 32, v108
	v_add_u32_e32 v111, 0x860, v108
	v_lshl_add_u64 v[60:61], s[96:97], 0, v[4:5]
	v_add_u32_e32 v128, 0, v10
	v_add_u32_e32 v129, 0, v12
	v_add_u32_e32 v130, 0, v14
	v_add_u32_e32 v131, 0, v15
	v_add_u32_e32 v132, 0, v16
	v_add_u32_e32 v133, 0, v17
	v_add_u32_e32 v134, 0, v18
	v_add_u32_e32 v135, 0, v19
	v_add_u32_e32 v136, 0, v20
	v_add_u32_e32 v137, 0, v21
	v_add_u32_e32 v138, 0, v22
	v_add_u32_e32 v139, 0, v23
	v_add_u32_e32 v140, 0, v24
	v_add_u32_e32 v141, 0, v25
	v_add_u32_e32 v156, 0, v26
	v_add_u32_e32 v157, 0, v13
	v_add_u32_e32 v158, v70, v27
	v_add_u32_e32 v159, v70, v11
	v_add_u32_e32 v160, v72, v142
	v_add_u32_e32 v161, v63, v161
	v_add_u32_e32 v162, v62, v162
	v_add_u32_e32 v163, v62, v6
	v_add_u32_e32 v164, v62, v7
	v_add_u32_e32 v165, v62, v8
	v_add_u32_e32 v166, v62, v9
	v_add_u32_e32 v167, v62, v2
	v_add_u32_e32 v168, v62, v0
	v_add_u32_e32 v169, v62, v169
	s_mov_b32 s2, s94
	v_readlane_b32 s98, v252, 14
	v_readlane_b32 s99, v252, 15
	s_nop 4
	v_mov_b32_e32 v230, s98
	v_mov_b32_e32 v231, s99
	v_mov_b32_e32 v232, s98
	v_mov_b32_e32 v233, s99
	v_mov_b32_e32 v234, s98
	v_mov_b32_e32 v235, s99
	v_mov_b32_e32 v236, s98
	v_mov_b32_e32 v237, s99
	v_mov_b32_e32 v238, s98
	v_mov_b32_e32 v239, s99
	v_mov_b32_e32 v240, s98
	v_mov_b32_e32 v241, s99
	s_nop 1
	s_mov_b32 s98, 0x100000
	s_mov_b32 s99, 0
	s_mov_b32 s100, 0x200000
	s_mov_b32 s101, 0
	s_branch .LBB0_609
.LBB0_608:
	s_or_b64 exec, exec, s[86:87]
	global_load_dword v254, v[230:231], off
	global_load_dword v254, v[232:233], off
	global_load_dword v254, v[234:235], off
	global_load_dword v254, v[236:237], off
	global_load_dword v254, v[238:239], off
	global_load_dword v254, v[240:241], off
	v_add_u32_e32 v0, v73, v84
	ds_write_b128 v0, v[4:7]
	v_add_u32_e32 v0, v73, v85
	ds_write_b128 v0, v[12:15]
	v_add_u32_e32 v0, v73, v86
	ds_write_b128 v0, v[8:11]
	v_add_u32_e32 v0, v73, v87
	ds_write_b128 v0, v[20:23]
	s_waitcnt lgkmcnt(0)
	s_barrier
	ds_read_b64_tr_b16 v[0:1], v88
	s_waitcnt lgkmcnt(0)
	ds_read_b64_tr_b16 v[2:3], v89
	s_waitcnt lgkmcnt(0)
	ds_read_b64_tr_b16 v[4:5], v90
	s_waitcnt lgkmcnt(0)
	ds_read_b64_tr_b16 v[6:7], v91
	s_waitcnt lgkmcnt(0)
	ds_read_b64_tr_b16 v[8:9], v92
	s_waitcnt lgkmcnt(0)
	ds_read_b64_tr_b16 v[10:11], v93
	s_waitcnt lgkmcnt(0)
	ds_read_b64_tr_b16 v[16:17], v94
	s_waitcnt lgkmcnt(0)
	ds_read_b64_tr_b16 v[18:19], v95
	s_waitcnt lgkmcnt(0)
	ds_read_b64_tr_b16 v[24:25], v96
	s_waitcnt lgkmcnt(0)
	ds_read_b64_tr_b16 v[26:27], v97
	s_waitcnt lgkmcnt(0)
	ds_read_b64_tr_b16 v[174:175], v98
	s_waitcnt lgkmcnt(0)
	ds_read_b64_tr_b16 v[176:177], v99
	s_waitcnt lgkmcnt(0)
	ds_read_b64_tr_b16 v[182:183], v100
	s_waitcnt lgkmcnt(0)
	ds_read_b64_tr_b16 v[184:185], v101
	s_waitcnt lgkmcnt(0)
	ds_read_b64_tr_b16 v[190:191], v102
	s_waitcnt lgkmcnt(0)
	ds_read_b64_tr_b16 v[192:193], v103
	s_waitcnt lgkmcnt(0)
	ds_read_b64_tr_b16 v[198:199], v104
	s_waitcnt lgkmcnt(0)
	ds_read_b64_tr_b16 v[200:201], v105
	s_waitcnt lgkmcnt(0)
	ds_read_b64_tr_b16 v[206:207], v106
	s_waitcnt lgkmcnt(0)
	ds_read_b64_tr_b16 v[208:209], v107
	s_waitcnt lgkmcnt(0)
	s_nop 0
	v_mfma_f32_16x16x32_bf16 v[12:15], v[8:11], v[0:3], 0
	s_lshl_b64 s[84:85], s[84:85], 16
	s_mov_b64 s[86:87], s[38:39]
	s_add_u32 s84, s86, s84
	v_mfma_f32_16x16x32_bf16 v[8:11], v[8:11], v[4:7], 0
	s_addc_u32 s85, s87, s85
	s_add_i32 s2, s2, s88
	s_cmpk_lt_i32 s2, 0x804
	v_mfma_f32_16x16x32_bf16 v[20:23], v[16:19], v[0:3], 0
	v_mfma_f32_16x16x32_bf16 v[16:19], v[16:19], v[4:7], 0
	v_mfma_f32_16x16x32_bf16 v[170:173], v[24:27], v[0:3], 0
	v_mfma_f32_16x16x32_bf16 v[24:27], v[24:27], v[4:7], 0
	v_mfma_f32_16x16x32_bf16 v[178:181], v[174:177], v[0:3], 0
	v_mfma_f32_16x16x32_bf16 v[174:177], v[174:177], v[4:7], 0
	v_mfma_f32_16x16x32_bf16 v[186:189], v[182:185], v[0:3], 0
	v_mfma_f32_16x16x32_bf16 v[182:185], v[182:185], v[4:7], 0
	v_mfma_f32_16x16x32_bf16 v[194:197], v[190:193], v[0:3], 0
	v_mfma_f32_16x16x32_bf16 v[190:193], v[190:193], v[4:7], 0
	v_mfma_f32_16x16x32_bf16 v[202:205], v[198:201], v[0:3], 0
	v_mfma_f32_16x16x32_bf16 v[198:201], v[198:201], v[4:7], 0
	v_mfma_f32_16x16x32_bf16 v[0:3], v[206:209], v[0:3], 0
	v_mfma_f32_16x16x32_bf16 v[4:7], v[206:209], v[4:7], 0
	ds_read_b64_tr_b16 v[206:207], v108
	s_waitcnt lgkmcnt(0)
	ds_read_b64_tr_b16 v[208:209], v109
	s_waitcnt lgkmcnt(0)
	ds_read_b64_tr_b16 v[210:211], v110
	s_waitcnt lgkmcnt(0)
	ds_read_b64_tr_b16 v[212:213], v111
	s_waitcnt lgkmcnt(0)
	ds_read_b64_tr_b16 v[214:215], v112
	s_waitcnt lgkmcnt(0)
	ds_read_b64_tr_b16 v[216:217], v113
	s_waitcnt lgkmcnt(0)
	s_nop 0
	v_mfma_f32_16x16x32_bf16 v[12:15], v[214:217], v[206:209], v[12:15]
	v_mfma_f32_16x16x32_bf16 v[8:11], v[214:217], v[210:213], v[8:11]
	ds_read_b64_tr_b16 v[214:215], v114
	s_waitcnt lgkmcnt(0)
	ds_read_b64_tr_b16 v[216:217], v115
	s_waitcnt lgkmcnt(0)
	s_nop 0
	v_mfma_f32_16x16x32_bf16 v[20:23], v[214:217], v[206:209], v[20:23]
	v_mfma_f32_16x16x32_bf16 v[16:19], v[214:217], v[210:213], v[16:19]
	ds_read_b64_tr_b16 v[214:215], v116
	s_waitcnt lgkmcnt(0)
	ds_read_b64_tr_b16 v[216:217], v117
	s_waitcnt lgkmcnt(0)
	s_nop 0
	v_mfma_f32_16x16x32_bf16 v[170:173], v[214:217], v[206:209], v[170:173]
	v_mfma_f32_16x16x32_bf16 v[24:27], v[214:217], v[210:213], v[24:27]
	ds_read_b64_tr_b16 v[214:215], v118
	s_waitcnt lgkmcnt(0)
	ds_read_b64_tr_b16 v[216:217], v119
	s_waitcnt lgkmcnt(0)
	s_nop 0
	v_mfma_f32_16x16x32_bf16 v[178:181], v[214:217], v[206:209], v[178:181]
	v_mfma_f32_16x16x32_bf16 v[174:177], v[214:217], v[210:213], v[174:177]
	ds_read_b64_tr_b16 v[214:215], v120
	s_waitcnt lgkmcnt(0)
	ds_read_b64_tr_b16 v[216:217], v121
	s_waitcnt lgkmcnt(0)
	s_nop 0
	v_mfma_f32_16x16x32_bf16 v[186:189], v[214:217], v[206:209], v[186:189]
	v_mfma_f32_16x16x32_bf16 v[182:185], v[214:217], v[210:213], v[182:185]
	ds_read_b64_tr_b16 v[214:215], v122
	s_waitcnt lgkmcnt(0)
	ds_read_b64_tr_b16 v[216:217], v123
	s_waitcnt lgkmcnt(0)
	s_nop 0
	v_mfma_f32_16x16x32_bf16 v[194:197], v[214:217], v[206:209], v[194:197]
	v_mfma_f32_16x16x32_bf16 v[190:193], v[214:217], v[210:213], v[190:193]
	ds_read_b64_tr_b16 v[214:215], v124
	s_waitcnt lgkmcnt(0)
	ds_read_b64_tr_b16 v[216:217], v125
	s_waitcnt lgkmcnt(0)
	s_nop 0
	v_mfma_f32_16x16x32_bf16 v[202:205], v[214:217], v[206:209], v[202:205]
	v_mfma_f32_16x16x32_bf16 v[198:201], v[214:217], v[210:213], v[198:201]
	ds_read_b64_tr_b16 v[214:215], v126
	s_waitcnt lgkmcnt(0)
	ds_read_b64_tr_b16 v[216:217], v127
	s_waitcnt lgkmcnt(0)
	s_barrier
	v_cvt_pk_bf16_f32 v12, v12, v13
	v_cvt_pk_bf16_f32 v13, v14, v15
	ds_write_b64 v161, v[12:13]
	v_cvt_pk_bf16_f32 v8, v8, v9
	v_cvt_pk_bf16_f32 v9, v10, v11
	ds_write_b64 v161, v[8:9] offset:4352
	v_cvt_pk_bf16_f32 v8, v20, v21
	v_cvt_pk_bf16_f32 v9, v22, v23
	ds_write_b64 v161, v[8:9] offset:32
	v_cvt_pk_bf16_f32 v8, v16, v17
	v_cvt_pk_bf16_f32 v9, v18, v19
	ds_write_b64 v161, v[8:9] offset:4384
	v_cvt_pk_bf16_f32 v8, v170, v171
	v_cvt_pk_bf16_f32 v9, v172, v173
	ds_write_b64 v161, v[8:9] offset:64
	v_cvt_pk_bf16_f32 v8, v24, v25
	v_cvt_pk_bf16_f32 v9, v26, v27
	ds_write_b64 v161, v[8:9] offset:4416
	v_cvt_pk_bf16_f32 v8, v178, v179
	v_cvt_pk_bf16_f32 v9, v180, v181
	ds_write_b64 v161, v[8:9] offset:96
	v_cvt_pk_bf16_f32 v8, v174, v175
	v_cvt_pk_bf16_f32 v9, v176, v177
	ds_write_b64 v161, v[8:9] offset:4448
	v_cvt_pk_bf16_f32 v8, v186, v187
	v_cvt_pk_bf16_f32 v9, v188, v189
	ds_write_b64 v161, v[8:9] offset:128
	v_cvt_pk_bf16_f32 v8, v182, v183
	v_cvt_pk_bf16_f32 v9, v184, v185
	ds_write_b64 v161, v[8:9] offset:4480
	v_cvt_pk_bf16_f32 v8, v194, v195
	v_cvt_pk_bf16_f32 v9, v196, v197
	ds_write_b64 v161, v[8:9] offset:160
	v_cvt_pk_bf16_f32 v8, v190, v191
	v_cvt_pk_bf16_f32 v9, v192, v193
	v_mfma_f32_16x16x32_bf16 v[0:3], v[214:217], v[206:209], v[0:3]
	ds_write_b64 v161, v[8:9] offset:4512
	v_cvt_pk_bf16_f32 v8, v202, v203
	v_cvt_pk_bf16_f32 v9, v204, v205
	ds_write_b64 v161, v[8:9] offset:192
	v_cvt_pk_bf16_f32 v8, v198, v199
	v_cvt_pk_bf16_f32 v9, v200, v201
	ds_write_b64 v161, v[8:9] offset:4544
	v_cvt_pk_bf16_f32 v0, v0, v1
	v_cvt_pk_bf16_f32 v1, v2, v3
	v_mfma_f32_16x16x32_bf16 v[4:7], v[214:217], v[210:213], v[4:7]
	s_nop 3
	ds_write_b64 v161, v[0:1] offset:224
	v_cvt_pk_bf16_f32 v0, v4, v5
	v_cvt_pk_bf16_f32 v1, v6, v7
	ds_write_b64 v161, v[0:1] offset:4576
	s_waitcnt lgkmcnt(0)
	s_barrier
	v_lshl_add_u64 v[4:5], s[84:85], 0, v[36:37]
	ds_read_b128 v[0:3], v169
	s_waitcnt lgkmcnt(0)
	global_store_dwordx4 v[4:5], v[0:3], off sc1
	s_nop 1
	v_lshl_add_u64 v[4:5], s[84:85], 0, v[46:47]
	ds_read_b128 v[0:3], v162
	s_waitcnt lgkmcnt(0)
	global_store_dwordx4 v[4:5], v[0:3], off sc1
	s_nop 1
	v_lshl_add_u64 v[4:5], s[84:85], 0, v[48:49]
	ds_read_b128 v[0:3], v163
	s_waitcnt lgkmcnt(0)
	global_store_dwordx4 v[4:5], v[0:3], off sc1
	s_nop 1
	v_lshl_add_u64 v[4:5], s[84:85], 0, v[50:51]
	ds_read_b128 v[0:3], v164
	s_waitcnt lgkmcnt(0)
	global_store_dwordx4 v[4:5], v[0:3], off sc1
	s_nop 1
	v_lshl_add_u64 v[4:5], s[84:85], 0, v[52:53]
	ds_read_b128 v[0:3], v165
	s_waitcnt lgkmcnt(0)
	global_store_dwordx4 v[4:5], v[0:3], off sc1
	s_nop 1
	v_lshl_add_u64 v[4:5], s[84:85], 0, v[54:55]
	ds_read_b128 v[0:3], v166
	s_waitcnt lgkmcnt(0)
	global_store_dwordx4 v[4:5], v[0:3], off sc1
	s_nop 1
	v_lshl_add_u64 v[4:5], s[84:85], 0, v[56:57]
	ds_read_b128 v[0:3], v167
	s_waitcnt lgkmcnt(0)
	global_store_dwordx4 v[4:5], v[0:3], off sc1
	s_nop 1
	v_lshl_add_u64 v[4:5], s[84:85], 0, v[58:59]
	ds_read_b128 v[0:3], v168
	s_waitcnt lgkmcnt(0)
	global_store_dwordx4 v[4:5], v[0:3], off sc1
	s_nop 1
	s_barrier
	s_cbranch_scc0 .LBB0_641

.LBB0_619:
	s_or_b64 exec, exec, s[84:85]
	v_readlane_b32 s4, v252, 0
	v_lshl_or_b32 v142, s95, 7, v66
	v_readlane_b32 s5, v252, 1
	v_readlane_b32 s6, v252, 2
	v_readlane_b32 s7, v252, 3
	v_readlane_b32 s8, v252, 4
	v_readlane_b32 s9, v252, 5
	v_lshlrev_b64 v[4:5], 2, v[142:143]
	v_readlane_b32 s10, v252, 6
	v_readlane_b32 s11, v252, 7
	v_readlane_b32 s12, v252, 8
	v_readlane_b32 s13, v252, 9
	s_mov_b64 s[4:5], s[8:9]
	v_lshl_add_u64 v[6:7], s[4:5], 0, v[4:5]
	v_add_co_u32_e32 v8, vcc, 0x1000, v6
	s_movk_i32 s20, 0x2000
	s_nop 0
	v_addc_co_u32_e32 v9, vcc, 0, v7, vcc
	global_load_dword v170, v[6:7], off
	global_load_dword v171, v[6:7], off offset:2048
	global_load_dword v173, v[8:9], off
	global_load_dword v172, v[8:9], off offset:2048
	v_add_co_u32_e32 v8, vcc, s20, v6
	s_movk_i32 s20, 0x4000
	s_nop 0
	v_addc_co_u32_e32 v9, vcc, 0, v7, vcc
	global_load_dword v174, v[8:9], off
	global_load_dword v175, v[8:9], off offset:2048
	v_add_co_u32_e32 v8, vcc, 0x3000, v6
	s_mov_b64 s[6:7], s[10:11]
	s_nop 0
	v_addc_co_u32_e32 v9, vcc, 0, v7, vcc
	global_load_dword v177, v[8:9], off
	global_load_dword v176, v[8:9], off offset:2048
	v_add_co_u32_e32 v8, vcc, s20, v6
	s_movk_i32 s20, 0x6000
	s_nop 0
	v_addc_co_u32_e32 v9, vcc, 0, v7, vcc
	global_load_dword v178, v[8:9], off
	global_load_dword v179, v[8:9], off offset:2048
	v_add_co_u32_e32 v8, vcc, 0x5000, v6
	v_lshl_add_u64 v[4:5], s[6:7], 0, v[4:5]
	s_nop 0
	v_addc_co_u32_e32 v9, vcc, 0, v7, vcc
	global_load_dword v181, v[8:9], off
	global_load_dword v180, v[8:9], off offset:2048
	v_add_co_u32_e32 v8, vcc, s20, v6
	s_movk_i32 s20, 0xffc0
	s_nop 0
	v_addc_co_u32_e32 v9, vcc, 0, v7, vcc
	v_add_co_u32_e32 v6, vcc, 0x7000, v6
	global_load_dword v182, v[8:9], off
	global_load_dword v183, v[8:9], off offset:2048
	v_addc_co_u32_e32 v7, vcc, 0, v7, vcc
	global_load_dword v185, v[6:7], off
	global_load_dword v184, v[6:7], off offset:2048
	global_load_dword v186, v[4:5], off
	s_cmp_eq_u32 s36, 0
	v_add3_u32 v20, v1, v2, s20
	s_cselect_b64 vcc, -1, 0
	v_add_u32_e32 v4, v20, v67
	s_lshl_b32 s20, s95, 8
	v_cndmask_b32_e32 v142, v4, v74, vcc
	v_lshl_add_u64 v[6:7], v[30:31], 0, s[20:21]
	v_cmp_lt_i32_e64 s[84:85], -1, v142
	v_mov_b32_e32 v1, 0
	v_mov_b32_e32 v2, 0
	v_mov_b32_e32 v3, 0
	v_readlane_b32 s14, v252, 10
	v_readlane_b32 s15, v252, 11
	v_readlane_b32 s16, v252, 12
	v_readlane_b32 s17, v252, 13
	v_readlane_b32 s18, v252, 14
	v_readlane_b32 s19, v252, 15
	s_mov_b64 s[8:9], s[12:13]
	s_and_saveexec_b64 s[86:87], s[84:85]
	s_cbranch_execz .LBB0_621
	v_lshlrev_b64 v[0:1], 10, v[142:143]
	v_lshl_add_u64 v[0:1], v[6:7], 0, v[0:1]
	v_lshl_add_u64 v[230:231], v[0:1], 0, s[98:99]
	global_load_dwordx4 v[0:3], v[0:1], off
.LBB0_621:
	s_or_b64 exec, exec, s[86:87]
	v_add_u32_e32 v4, 32, v4
	v_cndmask_b32_e32 v142, v4, v75, vcc
	v_cmp_lt_i32_e64 s[84:85], -1, v142
	v_mov_b32_e32 v4, 0
	v_mov_b32_e32 v16, 0
	v_mov_b32_e32 v17, 0
	v_mov_b32_e32 v18, 0
	v_mov_b32_e32 v19, 0
	s_and_saveexec_b64 s[86:87], s[84:85]
	s_cbranch_execz .LBB0_623
	v_lshlrev_b64 v[8:9], 10, v[142:143]
	v_lshl_add_u64 v[6:7], v[6:7], 0, v[8:9]
	v_lshl_add_u64 v[232:233], v[6:7], 0, s[98:99]
	global_load_dwordx4 v[16:19], v[6:7], off
.LBB0_623:
	s_or_b64 exec, exec, s[86:87]
	v_add_u32_e32 v5, v20, v76
	s_lshl_b32 s20, s95, 9
	v_cndmask_b32_e32 v142, v5, v77, vcc
	v_lshl_add_u64 v[62:63], v[32:33], 0, s[20:21]
	v_cmp_lt_i32_e64 s[84:85], -1, v142
	v_mov_b32_e32 v5, 0
	v_mov_b32_e32 v6, 0
	v_mov_b32_e32 v7, 0
	s_and_saveexec_b64 s[86:87], s[84:85]
	s_cbranch_execz .LBB0_625
	v_lshlrev_b64 v[4:5], 11, v[142:143]
	v_lshl_add_u64 v[4:5], v[62:63], 0, v[4:5]
	v_lshl_add_u64 v[234:235], v[4:5], 0, s[100:101]
	global_load_dwordx4 v[4:7], v[4:5], off
.LBB0_625:
	s_or_b64 exec, exec, s[86:87]
	v_add_u32_e32 v8, v20, v78
	v_cndmask_b32_e32 v142, v8, v79, vcc
	v_cmp_lt_i32_e64 s[84:85], -1, v142
	v_mov_b32_e32 v8, 0
	v_mov_b32_e32 v12, 0
	v_mov_b32_e32 v13, 0
	v_mov_b32_e32 v14, 0
	v_mov_b32_e32 v15, 0
	s_and_saveexec_b64 s[86:87], s[84:85]
	s_cbranch_execz .LBB0_627
	v_lshlrev_b64 v[10:11], 11, v[142:143]
	v_lshl_add_u64 v[10:11], v[62:63], 0, v[10:11]
	v_lshl_add_u64 v[236:237], v[10:11], 0, s[100:101]
	global_load_dwordx4 v[12:15], v[10:11], off
.LBB0_627:
	s_or_b64 exec, exec, s[86:87]
	v_add_u32_e32 v9, v20, v80
	v_cndmask_b32_e32 v142, v9, v81, vcc
	v_cmp_lt_i32_e64 s[84:85], -1, v142
	v_mov_b32_e32 v9, 0
	v_mov_b32_e32 v10, 0
	v_mov_b32_e32 v11, 0
	s_and_saveexec_b64 s[86:87], s[84:85]
	s_cbranch_execz .LBB0_629
	v_lshlrev_b64 v[8:9], 11, v[142:143]
	v_lshl_add_u64 v[8:9], v[62:63], 0, v[8:9]
	v_lshl_add_u64 v[238:239], v[8:9], 0, s[100:101]
	global_load_dwordx4 v[8:11], v[8:9], off
.LBB0_629:
	s_or_b64 exec, exec, s[86:87]
	v_add_u32_e32 v20, v20, v82
	v_cndmask_b32_e32 v142, v20, v83, vcc
	v_cmp_lt_i32_e64 s[84:85], -1, v142
	v_mov_b32_e32 v20, 0
	v_mov_b32_e32 v21, 0
	v_mov_b32_e32 v22, 0
	v_mov_b32_e32 v23, 0
	s_and_saveexec_b64 s[86:87], s[84:85]
	s_cbranch_execz .LBB0_631
	v_lshlrev_b64 v[20:21], 11, v[142:143]
	v_lshl_add_u64 v[20:21], v[62:63], 0, v[20:21]
	v_lshl_add_u64 v[240:241], v[20:21], 0, s[100:101]
	global_load_dwordx4 v[20:23], v[20:21], off

.LBB0_752:
	s_or_b64 exec, exec, s[38:39]
	v_readlane_b32 s4, v251, 27
	s_waitcnt lgkmcnt(0)
	v_mov_b32_e32 v0, v222
	v_readlane_b32 s5, v251, 28
	s_barrier
	s_and_b64 vcc, exec, s[4:5]
	v_readfirstlane_b32 s2, v0
	s_cbranch_vccz .LBB0_812
	s_ashr_i32 s20, s2, 6
	v_lshlrev_b32_e32 v11, 3, v0
	v_lshlrev_b32_e32 v2, 4, v0
	v_and_b32_e32 v12, 0x78, v11
	v_readlane_b32 s4, v251, 11
	s_lshl_b32 s28, s20, 5
	v_and_b32_e32 v142, 0x1f0, v2
	v_lshlrev_b32_e32 v2, 1, v12
	v_mov_b32_e32 v3, v143
	v_readlane_b32 s5, v251, 12
	s_ashr_i32 s29, s28, 31
	s_lshl_b64 s[36:37], s[28:29], 2
	v_lshl_add_u64 v[92:93], s[4:5], 0, v[2:3]
	v_readlane_b32 s4, v251, 13
	v_readlane_b32 s5, v251, 14
	s_add_u32 s36, s60, s36
	s_addc_u32 s37, s61, s37
	v_lshl_add_u64 v[94:95], s[4:5], 0, v[142:143]
	s_lshl_b64 s[28:29], s[28:29], 1
	v_readlane_b32 s4, v251, 15
	v_bfe_u32 v8, v0, 4, 2
	v_and_b32_e32 v6, 48, v0
	v_mov_b32_e32 v7, v143
	v_readlane_b32 s5, v251, 16
	s_add_u32 s28, s4, s28
	v_and_b32_e32 v158, 15, v0
	v_and_b32_e32 v1, 63, v0
	v_lshlrev_b32_e32 v4, 3, v8
	v_mov_b32_e32 v5, v143
	v_lshl_add_u64 v[98:99], s[36:37], 0, v[6:7]
	s_addc_u32 s29, s5, s29
	s_ashr_i32 s36, s2, 7
	v_lshl_add_u32 v9, v1, 2, 0
	v_lshlrev_b32_e32 v10, 2, v0
	v_ashrrev_i32_e32 v159, 4, v0
	v_lshl_add_u64 v[90:91], s[0:1], 0, v[2:3]
	v_lshl_add_u64 v[96:97], s[86:87], 0, v[6:7]
	v_lshlrev_b32_e32 v3, 2, v8
	v_lshl_add_u64 v[100:101], s[28:29], 0, v[4:5]
	s_lshl_b32 s28, s20, 1
	v_lshl_or_b32 v7, s36, 4, v158
	v_add_u32_e32 v8, 0, v6
	s_movk_i32 s6, 0x110
	s_and_b32 s37, s28, 2
	v_mad_u64_u32 v[102:103], s[28:29], v7, s6, v[8:9]
	v_and_b32_e32 v104, 0xffffff80, v10
	v_add_u32_e32 v10, 0x7fd0, v159
	v_cmp_lt_i32_e32 vcc, 47, v159
	v_ashrrev_i32_e32 v164, 5, v0
	v_bfe_u32 v13, v0, 2, 2
	v_cndmask_b32_e32 v103, -1, v10, vcc
	v_add_u32_e32 v10, 0x7ff0, v159
	v_cmp_lt_i32_e32 vcc, 15, v159
	v_readlane_b32 s5, v250, 43
	s_movk_i32 s28, 0x90
	v_cndmask_b32_e32 v163, -1, v10, vcc
	v_add_u32_e32 v10, 0x7fd0, v164
	v_cmp_lt_i32_e32 vcc, 47, v164
	s_andn2_b32 s2, s2, 63
	v_lshl_add_u32 v161, v12, 2, 0
	v_cndmask_b32_e32 v165, -1, v10, vcc
	v_add_u32_e32 v10, 0x200, v0
	v_ashrrev_i32_e32 v166, 5, v10
	v_add_u32_e32 v10, 0x7fd0, v166
	v_cmp_lt_i32_e32 vcc, 47, v166
	v_mul_lo_u32 v12, v7, s28
	s_lshl_b32 s28, s20, 8
	v_cndmask_b32_e32 v167, -1, v10, vcc
	v_add_u32_e32 v10, 0x400, v0
	v_ashrrev_i32_e32 v168, 5, v10
	v_add_u32_e32 v0, 0x600, v0
	v_add_u32_e32 v10, 0x7fd0, v168
	v_cmp_lt_i32_e32 vcc, 47, v168
	v_ashrrev_i32_e32 v170, 5, v0
	s_add_i32 s29, s5, s2
	v_cndmask_b32_e32 v169, -1, v10, vcc
	v_add_u32_e32 v0, 0x7fd0, v170
	v_cmp_lt_i32_e32 vcc, 47, v170
	s_cmp_le_i32 s37, s36
	s_cselect_b64 s[66:67], -1, 0
	v_cndmask_b32_e32 v171, -1, v0, vcc
	v_lshlrev_b32_e32 v0, 7, v158
	v_lshl_or_b32 v112, s20, 12, v0
	s_lshl_b32 s20, s37, 4
	v_sub_u32_e32 v5, v161, v2
	v_cmp_gt_u32_e64 s[38:39], 16, v1
	v_or_b32_e32 v174, 48, v1
	v_mul_lo_u32 v1, v159, s6
	s_cmp_lt_i32 s37, s36
	v_or_b32_e32 v17, s20, v3
	v_or_b32_e32 v13, v4, v13
	v_readlane_b32 s7, v250, 44
	v_add_u32_e32 v4, s29, v4
	s_movk_i32 s4, 0x210
	v_add_u32_e32 v180, v5, v1
	s_cselect_b64 s[68:69], -1, 0
	s_or_b32 s29, s20, 16
	v_mov_b32_e32 v5, s5
	v_or_b32_e32 v18, 2, v17
	v_readlane_b32 s8, v250, 45
	v_add3_u32 v181, s7, v2, v1
	v_or_b32_e32 v1, s20, v158
	v_or_b32_e32 v2, s29, v158
	v_mad_u32_u24 v5, v13, s4, v5
	v_and_b32_e32 v10, 24, v11
	v_cmp_gt_i32_e64 s[40:41], v17, v7
	v_cmp_lt_i32_e64 s[42:43], v17, v7
	v_cmp_gt_i32_e64 s[44:45], v18, v7
	v_or_b32_e32 v18, 3, v17
	v_lshlrev_b32_e32 v17, 1, v17
	v_or_b32_e32 v3, s29, v3
	v_add_u32_e32 v14, s8, v6
	v_add_u32_e32 v6, s7, v6
	v_add_u32_e32 v106, 0x800, v104
	v_add_u32_e32 v108, 0x1000, v104
	v_add_u32_e32 v110, 0x1800, v104
	v_or_b32_e32 v114, 0x800, v112
	v_mul_lo_u32 v0, v159, s4
	v_mul_u32_u24_e32 v1, 0x110, v1
	v_mul_u32_u24_e32 v2, 0x110, v2
	v_add3_u32 v184, v5, v10, s2
	v_mul_u32_u24_e32 v5, 0x90, v158
	v_mul_u32_u24_e32 v10, 0x90, v174
	v_mul_u32_u24_e32 v11, 0x110, v158
	v_mul_u32_u24_e32 v13, 0x110, v174
	v_mul_u32_u24_e32 v15, 0x210, v158
	v_mul_u32_u24_e32 v16, 0x210, v174
	v_add3_u32 v194, s8, v12, v17
	v_cmp_gt_i32_e64 s[48:49], v3, v7
	v_cmp_lt_i32_e64 s[50:51], v3, v7
	v_or_b32_e32 v12, 2, v3
	v_or_b32_e32 v3, 3, v3
	v_lshl_add_u64 v[88:89], s[96:97], 0, v[142:143]
	v_add_u32_e32 v160, 0, v142
	v_add_u32_e32 v162, s5, v142
	v_ashrrev_i32_e32 v105, 31, v104
	v_ashrrev_i32_e32 v107, 31, v106
	v_ashrrev_i32_e32 v109, 31, v108
	v_ashrrev_i32_e32 v111, 31, v110
	v_ashrrev_i32_e32 v113, 31, v112
	v_ashrrev_i32_e32 v115, 31, v114
	v_or_b32_e32 v172, 16, v158
	v_or_b32_e32 v173, 32, v158
	v_add_u32_e32 v175, 0x7fd0, v174
	v_mul_lo_u32 v176, v164, s4
	v_mul_lo_u32 v177, v166, s4
	v_mul_lo_u32 v178, v168, s4
	v_mul_lo_u32 v179, v170, s4
	v_add_u32_e32 v182, 0x2200, v180
	v_add_u32_e32 v183, 0x2200, v181
	v_add_u32_e32 v185, 0x840, v184
	v_add_u32_e32 v186, 32, v184
	v_add_u32_e32 v187, 0x860, v184
	v_add_u32_e32 v188, 0x4200, v184
	v_add_u32_e32 v189, 0x4a40, v184
	v_add_u32_e32 v190, 0x4220, v184
	v_add_u32_e32 v191, 0x4a60, v184
	v_lshl_add_u32 v192, v158, 2, 0
	v_lshl_add_u32 v193, v174, 2, 0
	v_cmp_gt_i32_e64 s[46:47], v18, v7
	v_cmp_gt_i32_e64 s[52:53], v12, v7
	v_cmp_gt_i32_e64 s[54:55], v3, v7
	v_add_u32_e32 v195, v161, v0
	v_add_u32_e32 v196, v8, v1
	v_add_u32_e32 v197, v8, v2
	v_add_u32_e32 v198, v14, v5
	v_add_u32_e32 v199, v14, v10
	v_add_u32_e32 v200, v6, v11
	v_add_u32_e32 v201, v6, v13
	v_add_u32_e32 v202, v4, v15
	v_add_u32_e32 v203, v4, v16
	v_add_u32_e32 v204, s28, v9
	s_mov_b32 s2, s94
	v_readlane_b32 s98, v252, 14
	v_readlane_b32 s99, v252, 15
	s_nop 4
	v_mov_b32_e32 v210, s98
	v_mov_b32_e32 v211, s99
	v_mov_b32_e32 v212, s98
	v_mov_b32_e32 v213, s99
	v_mov_b32_e32 v214, s98
	v_mov_b32_e32 v215, s99
	v_mov_b32_e32 v216, s98
	v_mov_b32_e32 v217, s99
	v_mov_b32_e32 v218, s98
	v_mov_b32_e32 v219, s99
	v_mov_b32_e32 v220, s98
	v_mov_b32_e32 v221, s99
	v_mov_b32_e32 v230, s98
	v_mov_b32_e32 v231, s99
	v_mov_b32_e32 v232, s98
	v_mov_b32_e32 v233, s99
	v_mov_b32_e32 v234, s98
	v_mov_b32_e32 v235, s99
	v_mov_b32_e32 v236, s98
	v_mov_b32_e32 v237, s99
	v_mov_b32_e32 v238, s98
	v_mov_b32_e32 v239, s99
	v_mov_b32_e32 v240, s98
	v_mov_b32_e32 v241, s99
	v_mov_b32_e32 v242, s98
	v_mov_b32_e32 v243, s99
	v_mov_b32_e32 v244, s98
	v_mov_b32_e32 v245, s99
	s_nop 1
	s_mov_b32 s98, 0x100000
	s_mov_b32 s99, 0
	s_mov_b32 s100, 0x200000
	s_mov_b32 s101, 0
	s_branch .LBB0_755

.LBB0_759:
	s_lshl_b32 s28, s20, 4
	s_lshl_b32 s29, s36, 2
	s_or_b32 s28, s29, s28
	s_add_i32 s72, s28, s37
	s_ashr_i32 s73, s72, 31
	s_lshl_b64 s[28:29], s[72:73], 15
	v_lshl_add_u64 v[32:33], v[88:89], 0, s[28:29]
	v_lshl_add_u64 v[34:35], v[104:105], 2, v[32:33]
	v_lshl_add_u64 v[36:37], v[106:107], 2, v[32:33]
	v_lshl_add_u64 v[210:211], s[100:101], 2, v[34:35]
	global_load_dwordx4 v[68:71], v[34:35], off
	v_lshl_add_u64 v[212:213], s[100:101], 2, v[36:37]
	global_load_dwordx4 v[64:67], v[36:37], off
	v_lshl_add_u64 v[34:35], v[108:109], 2, v[32:33]
	v_lshl_add_u64 v[32:33], v[110:111], 2, v[32:33]
	v_lshl_add_u64 v[214:215], s[100:101], 2, v[34:35]
	global_load_dwordx4 v[76:79], v[34:35], off
	v_lshl_add_u64 v[216:217], s[100:101], 2, v[32:33]
	global_load_dwordx4 v[72:75], v[32:33], off
	s_cmp_eq_u32 s20, 0
	s_cselect_b64 s[64:65], -1, 0
	s_cmp_lg_u32 s20, 0
	s_cselect_b64 s[70:71], -1, 0
	s_lshl_b32 s28, s36, 13
	s_lshl_b32 s20, s20, 6
	s_add_i32 s20, s20, s28
	s_sub_i32 s36, s20, 64
	v_add_u32_e32 v36, s36, v159
	s_lshl_b32 s20, s37, 8
	v_cndmask_b32_e64 v142, v36, v103, s[64:65]
	v_lshl_add_u64 v[32:33], v[90:91], 0, s[20:21]
	v_lshl_add_u64 v[34:35], v[92:93], 0, s[20:21]
	v_cmp_lt_i32_e32 vcc, -1, v142
	v_mov_b32_e32 v40, 0
	v_mov_b32_e32 v84, 0
	v_mov_b32_e32 v85, 0
	v_mov_b32_e32 v86, 0
	v_mov_b32_e32 v87, 0
	v_mov_b32_e32 v80, 0
	v_mov_b32_e32 v81, 0
	v_mov_b32_e32 v82, 0
	v_mov_b32_e32 v83, 0
	s_and_saveexec_b64 s[56:57], vcc
	s_cbranch_execz .LBB0_761
	v_lshlrev_b64 v[38:39], 10, v[142:143]
	v_lshl_add_u64 v[42:43], v[34:35], 0, v[38:39]
	v_lshl_add_u64 v[38:39], v[32:33], 0, v[38:39]
	v_lshl_add_u64 v[218:219], s[98:99], 0, v[38:39]
	global_load_dwordx4 v[84:87], v[38:39], off
	v_lshl_add_u64 v[220:221], s[98:99], 0, v[42:43]
	global_load_dwordx4 v[80:83], v[42:43], off
.LBB0_761:
	s_or_b64 exec, exec, s[56:57]
	v_add_u32_e32 v36, 32, v36
	v_cndmask_b32_e64 v142, v36, v163, s[64:65]
	v_cmp_lt_i32_e32 vcc, -1, v142
	v_mov_b32_e32 v60, 0
	v_mov_b32_e32 v61, 0
	v_mov_b32_e32 v62, 0
	v_mov_b32_e32 v63, 0
	v_mov_b32_e32 v56, 0
	v_mov_b32_e32 v57, 0
	v_mov_b32_e32 v58, 0
	v_mov_b32_e32 v59, 0
	s_and_saveexec_b64 s[56:57], vcc
	s_cbranch_execz .LBB0_763
	v_lshlrev_b64 v[36:37], 10, v[142:143]
	v_lshl_add_u64 v[32:33], v[32:33], 0, v[36:37]
	v_lshl_add_u64 v[34:35], v[34:35], 0, v[36:37]
	v_lshl_add_u64 v[230:231], s[98:99], 0, v[32:33]
	global_load_dwordx4 v[60:63], v[32:33], off
	v_lshl_add_u64 v[232:233], s[98:99], 0, v[34:35]
	global_load_dwordx4 v[56:59], v[34:35], off
.LBB0_763:
	s_or_b64 exec, exec, s[56:57]
	v_add_u32_e32 v32, s36, v164
	s_lshl_b32 s28, s37, 9
	s_mov_b32 s29, s21
	v_cndmask_b32_e64 v124, v32, v165, s[64:65]
	v_lshl_add_u64 v[116:117], v[94:95], 0, s[28:29]
	v_cmp_lt_i32_e64 s[62:63], -1, v124
	v_mov_b32_e32 v41, 0
	v_mov_b32_e32 v42, 0
	v_mov_b32_e32 v43, 0
	s_and_saveexec_b64 s[56:57], s[62:63]
	s_cbranch_execz .LBB0_765
	v_mov_b32_e32 v125, v143
	v_lshlrev_b64 v[32:33], 11, v[124:125]
	v_lshl_add_u64 v[32:33], v[116:117], 0, v[32:33]
	v_lshl_add_u64 v[234:235], s[100:101], 0, v[32:33]
	global_load_dwordx4 v[40:43], v[32:33], off
.LBB0_765:
	s_or_b64 exec, exec, s[56:57]
	v_add_u32_e32 v32, s36, v166
	v_cndmask_b32_e64 v122, v32, v167, s[64:65]
	v_cmp_lt_i32_e64 s[60:61], -1, v122
	v_mov_b32_e32 v44, 0
	v_mov_b32_e32 v48, 0
	v_mov_b32_e32 v49, 0
	v_mov_b32_e32 v50, 0
	v_mov_b32_e32 v51, 0
	s_and_saveexec_b64 s[56:57], s[60:61]
	s_cbranch_execz .LBB0_767
	v_mov_b32_e32 v123, v143
	v_lshlrev_b64 v[32:33], 11, v[122:123]
	v_lshl_add_u64 v[32:33], v[116:117], 0, v[32:33]
	v_lshl_add_u64 v[236:237], s[100:101], 0, v[32:33]
	global_load_dwordx4 v[48:51], v[32:33], off
.LBB0_767:
	s_or_b64 exec, exec, s[56:57]
	v_add_u32_e32 v32, s36, v168
	v_cndmask_b32_e64 v120, v32, v169, s[64:65]
	v_cmp_lt_i32_e64 s[58:59], -1, v120
	v_mov_b32_e32 v45, 0
	v_mov_b32_e32 v46, 0
	v_mov_b32_e32 v47, 0
	s_and_saveexec_b64 s[56:57], s[58:59]
	s_cbranch_execz .LBB0_769
	v_mov_b32_e32 v121, v143
	v_lshlrev_b64 v[32:33], 11, v[120:121]
	v_lshl_add_u64 v[32:33], v[116:117], 0, v[32:33]
	v_lshl_add_u64 v[238:239], s[100:101], 0, v[32:33]
	global_load_dwordx4 v[44:47], v[32:33], off
.LBB0_769:
	s_or_b64 exec, exec, s[56:57]
	v_add_u32_e32 v32, s36, v170
	v_cndmask_b32_e64 v118, v32, v171, s[64:65]
	v_cmp_lt_i32_e64 s[56:57], -1, v118
	v_mov_b32_e32 v52, 0
	v_mov_b32_e32 v53, 0
	v_mov_b32_e32 v54, 0
	v_mov_b32_e32 v55, 0
	s_and_saveexec_b64 s[74:75], s[56:57]
	s_cbranch_execz .LBB0_771
	v_mov_b32_e32 v119, v143
	v_lshlrev_b64 v[32:33], 11, v[118:119]
	v_lshl_add_u64 v[32:33], v[116:117], 0, v[32:33]
	v_lshl_add_u64 v[240:241], s[100:101], 0, v[32:33]
	global_load_dwordx4 v[52:55], v[32:33], off
.LBB0_771:
	s_or_b64 exec, exec, s[74:75]
	s_and_b64 vcc, exec, s[70:71]
	s_cbranch_vccz .LBB0_773
	s_lshl_b64 s[28:29], s[72:73], 16
	v_lshl_add_u64 v[0:1], v[96:97], 0, s[28:29]
	v_lshl_add_u64 v[20:21], v[112:113], 1, v[0:1]
	v_lshl_add_u64 v[28:29], v[114:115], 1, v[0:1]
	s_cmpk_lt_u32 s72, 0x710
	s_cselect_b32 s28, 0x1000000, 0
	s_mov_b32 s29, 0
	v_lshl_add_u64 v[242:243], s[28:29], 0, v[20:21]
	global_load_dwordx4 v[0:3], v[20:21], off
	global_load_dwordx4 v[8:11], v[20:21], off offset:64
	v_lshl_add_u64 v[244:245], s[28:29], 0, v[28:29]
	global_load_dwordx4 v[4:7], v[28:29], off
	global_load_dwordx4 v[12:15], v[28:29], off offset:64
	global_load_dwordx4 v[16:19], v[20:21], off offset:128
	global_load_dwordx4 v[24:27], v[20:21], off offset:192
	s_nop 0
	global_load_dwordx4 v[20:23], v[28:29], off offset:128
	s_nop 0
	global_load_dwordx4 v[28:31], v[28:29], off offset:192

.LBB0_803:
	s_or_b64 exec, exec, s[64:65]
	s_waitcnt lgkmcnt(0)
	s_barrier
	ds_read2st64_b32 v[76:77], v192 offset0:156 offset1:157
	s_waitcnt lgkmcnt(0)
	v_add_f32_e32 v76, 0, v76
	v_add_f32_e32 v78, v76, v77
	ds_read2st64_b32 v[76:77], v192 offset0:158 offset1:159
	s_waitcnt lgkmcnt(0)
	v_add_f32_e32 v76, v78, v76
	v_add_f32_e32 v78, v76, v77
	ds_read2st64_b32 v[76:77], v192 offset0:160 offset1:161
	s_waitcnt lgkmcnt(0)
	v_add_f32_e32 v76, v78, v76
	v_add_f32_e32 v78, v76, v77
	ds_read2st64_b32 v[76:77], v192 offset0:162 offset1:163
	s_waitcnt lgkmcnt(0)
	v_add_f32_e32 v76, v78, v76
	v_add_f32_e32 v76, v76, v77
	v_fmamk_f32 v76, v76, 0x3b800000, v226
	v_cmp_gt_f32_e32 vcc, s83, v76
	v_mul_f32_e32 v77, 0x4f800000, v76
	s_nop 0
	v_cndmask_b32_e32 v76, v76, v77, vcc
	v_sqrt_f32_e32 v77, v76
	s_nop 0
	v_add_u32_e32 v78, -1, v77
	v_fma_f32 v79, -v78, v77, v76
	v_cmp_ge_f32_e64 s[64:65], 0, v79
	v_add_u32_e32 v79, 1, v77
	s_nop 0
	v_cndmask_b32_e64 v78, v77, v78, s[64:65]
	v_fma_f32 v77, -v79, v77, v76
	v_cmp_lt_f32_e64 s[64:65], 0, v77
	s_nop 1
	v_cndmask_b32_e64 v77, v78, v79, s[64:65]
	v_mul_f32_e32 v78, 0x37800000, v77
	v_cndmask_b32_e32 v77, v77, v78, vcc
	v_cmp_class_f32_e32 vcc, v76, v225
	s_nop 1
	v_cndmask_b32_e32 v76, v77, v76, vcc
	v_div_scale_f32 v77, s[28:29], v76, v76, 1.0
	v_rcp_f32_e32 v78, v77
	s_nop 0
	v_fma_f32 v79, -v77, v78, 1.0
	v_fmac_f32_e32 v78, v79, v78
	v_div_scale_f32 v79, vcc, 1.0, v76, 1.0
	v_mul_f32_e32 v80, v79, v78
	v_fma_f32 v81, -v77, v80, v79
	v_fmac_f32_e32 v80, v81, v78
	v_fma_f32 v77, -v77, v80, v79
	v_div_fmas_f32 v77, v77, v78, v80
	v_div_fixup_f32 v76, v77, v76, 1.0
	v_mul_f32_e32 v68, v68, v76
	s_waitcnt vmcnt(1)
	v_mul_f32_e32 v68, v36, v68
	s_waitcnt vmcnt(0)
	global_load_dword v254, v[210:211], off
	global_load_dword v254, v[212:213], off
	global_load_dword v254, v[214:215], off
	global_load_dword v254, v[216:217], off
	global_load_dword v254, v[218:219], off
	global_load_dword v254, v[220:221], off
	global_load_dword v254, v[230:231], off
	global_load_dword v254, v[232:233], off
	global_load_dword v254, v[234:235], off
	global_load_dword v254, v[236:237], off
	global_load_dword v254, v[238:239], off
	global_load_dword v254, v[240:241], off
	global_load_dword v254, v[242:243], off
	global_load_dword v254, v[242:243], off offset:128
	global_load_dword v254, v[244:245], off
	global_load_dword v254, v[244:245], off offset:128
	v_lshlrev_b32_e32 v77, 16, v140
	v_mul_f32_e32 v69, v69, v76
	v_mul_f32_e32 v68, v68, v77
	v_mul_f32_e32 v69, v37, v69
	v_and_b32_e32 v77, 0xffff0000, v140
	v_mul_f32_e32 v70, v70, v76
	v_mul_f32_e32 v69, v69, v77
	v_mul_f32_e32 v70, v38, v70
	v_lshlrev_b32_e32 v77, 16, v141
	v_mul_f32_e32 v71, v71, v76
	v_mul_f32_e32 v70, v70, v77
	v_mul_f32_e32 v71, v39, v71
	v_and_b32_e32 v77, 0xffff0000, v141
	v_cvt_pk_bf16_f32 v68, v68, v69
	v_mul_f32_e32 v64, v64, v76
	v_mul_f32_e32 v71, v71, v77
	v_cvt_pk_bf16_f32 v69, v70, v71
	ds_write_b64 v202, v[68:69]
	v_mul_f32_e32 v64, v32, v64
	v_lshlrev_b32_e32 v68, 16, v138
	v_mul_f32_e32 v65, v65, v76
	v_mul_f32_e32 v64, v64, v68
	v_mul_f32_e32 v65, v33, v65
	v_and_b32_e32 v68, 0xffff0000, v138
	v_mul_f32_e32 v66, v66, v76
	v_mul_f32_e32 v65, v65, v68
	v_mul_f32_e32 v66, v34, v66
	v_lshlrev_b32_e32 v68, 16, v139
	v_mul_f32_e32 v67, v67, v76
	v_mul_f32_e32 v66, v66, v68
	v_mul_f32_e32 v67, v35, v67
	v_and_b32_e32 v68, 0xffff0000, v139
	v_mul_f32_e32 v67, v67, v68
	v_cvt_pk_bf16_f32 v64, v64, v65
	v_cvt_pk_bf16_f32 v65, v66, v67
	ds_write_b64 v202, v[64:65] offset:32
	v_add_u32_e32 v66, 64, v192
	ds_read2st64_b32 v[64:65], v66 offset0:156 offset1:157
	s_waitcnt lgkmcnt(0)
	v_add_f32_e32 v64, 0, v64
	v_add_f32_e32 v67, v64, v65
	ds_read2st64_b32 v[64:65], v66 offset0:158 offset1:159
	s_waitcnt lgkmcnt(0)
	v_add_f32_e32 v64, v67, v64
	v_add_f32_e32 v67, v64, v65
	ds_read2st64_b32 v[64:65], v66 offset0:160 offset1:161
	s_waitcnt lgkmcnt(0)
	v_add_f32_e32 v64, v67, v64
	v_add_f32_e32 v67, v64, v65
	ds_read2st64_b32 v[64:65], v66 offset0:162 offset1:163
	s_waitcnt lgkmcnt(0)
	v_add_f32_e32 v64, v67, v64
	v_add_f32_e32 v64, v64, v65
	v_fmamk_f32 v64, v64, 0x3b800000, v226
	v_cmp_gt_f32_e32 vcc, s83, v64
	v_mul_f32_e32 v65, 0x4f800000, v64
	s_nop 0
	v_cndmask_b32_e32 v64, v64, v65, vcc
	v_sqrt_f32_e32 v65, v64
	s_nop 0
	v_add_u32_e32 v66, -1, v65
	v_fma_f32 v67, -v66, v65, v64
	v_cmp_ge_f32_e64 s[64:65], 0, v67
	v_add_u32_e32 v67, 1, v65
	s_nop 0
	v_cndmask_b32_e64 v66, v65, v66, s[64:65]
	v_fma_f32 v65, -v67, v65, v64
	v_cmp_lt_f32_e64 s[64:65], 0, v65
	s_nop 1
	v_cndmask_b32_e64 v65, v66, v67, s[64:65]
	v_mul_f32_e32 v66, 0x37800000, v65
	v_cndmask_b32_e32 v65, v65, v66, vcc
	v_cmp_class_f32_e32 vcc, v64, v225
	s_nop 1
	v_cndmask_b32_e32 v64, v65, v64, vcc
	v_div_scale_f32 v65, s[28:29], v64, v64, 1.0
	v_rcp_f32_e32 v66, v65
	s_nop 0
	v_fma_f32 v67, -v65, v66, 1.0
	v_fmac_f32_e32 v66, v67, v66
	v_div_scale_f32 v67, vcc, 1.0, v64, 1.0
	v_mul_f32_e32 v68, v67, v66
	v_fma_f32 v69, -v65, v68, v67
	v_fmac_f32_e32 v68, v69, v66
	v_fma_f32 v65, -v65, v68, v67
	v_div_fmas_f32 v65, v65, v66, v68
	v_div_fixup_f32 v64, v65, v64, 1.0
	v_mul_f32_e32 v60, v60, v64
	v_mul_f32_e32 v60, v36, v60
	v_lshlrev_b32_e32 v65, 16, v136
	v_mul_f32_e32 v61, v61, v64
	v_mul_f32_e32 v60, v60, v65
	v_mul_f32_e32 v61, v37, v61
	v_and_b32_e32 v65, 0xffff0000, v136
	v_mul_f32_e32 v62, v62, v64
	v_mul_f32_e32 v61, v61, v65
	v_mul_f32_e32 v62, v38, v62
	v_lshlrev_b32_e32 v65, 16, v137
	v_mul_f32_e32 v63, v63, v64
	v_mul_f32_e32 v62, v62, v65
	v_mul_f32_e32 v63, v39, v63
	v_and_b32_e32 v65, 0xffff0000, v137
	v_cvt_pk_bf16_f32 v60, v60, v61
	v_mul_f32_e32 v56, v56, v64
	v_mul_f32_e32 v63, v63, v65
	v_cvt_pk_bf16_f32 v61, v62, v63
	ds_write_b64 v202, v[60:61] offset:8448
	v_mul_f32_e32 v56, v32, v56
	v_lshlrev_b32_e32 v60, 16, v134
	v_mul_f32_e32 v57, v57, v64
	v_mul_f32_e32 v56, v56, v60
	v_mul_f32_e32 v57, v33, v57
	v_and_b32_e32 v60, 0xffff0000, v134
	v_mul_f32_e32 v58, v58, v64
	v_mul_f32_e32 v57, v57, v60
	v_mul_f32_e32 v58, v34, v58
	v_lshlrev_b32_e32 v60, 16, v135
	v_mul_f32_e32 v59, v59, v64
	v_mul_f32_e32 v58, v58, v60
	v_mul_f32_e32 v59, v35, v59
	v_and_b32_e32 v60, 0xffff0000, v135
	v_mul_f32_e32 v59, v59, v60
	v_cvt_pk_bf16_f32 v56, v56, v57
	v_cvt_pk_bf16_f32 v57, v58, v59
	ds_write_b64 v202, v[56:57] offset:8480
	v_add_u32_e32 v58, 0x80, v192
	ds_read2st64_b32 v[56:57], v58 offset0:156 offset1:157
	s_waitcnt lgkmcnt(0)
	v_add_f32_e32 v56, 0, v56
	v_add_f32_e32 v59, v56, v57
	ds_read2st64_b32 v[56:57], v58 offset0:158 offset1:159
	s_waitcnt lgkmcnt(0)
	v_add_f32_e32 v56, v59, v56
	v_add_f32_e32 v59, v56, v57
	ds_read2st64_b32 v[56:57], v58 offset0:160 offset1:161
	s_waitcnt lgkmcnt(0)
	v_add_f32_e32 v56, v59, v56
	v_add_f32_e32 v59, v56, v57
	ds_read2st64_b32 v[56:57], v58 offset0:162 offset1:163
	s_waitcnt lgkmcnt(0)
	v_add_f32_e32 v56, v59, v56
	v_add_f32_e32 v56, v56, v57
	v_fmamk_f32 v56, v56, 0x3b800000, v226
	v_cmp_gt_f32_e32 vcc, s83, v56
	v_mul_f32_e32 v57, 0x4f800000, v56
	s_nop 0
	v_cndmask_b32_e32 v56, v56, v57, vcc
	v_sqrt_f32_e32 v57, v56
	s_nop 0
	v_add_u32_e32 v58, -1, v57
	v_fma_f32 v59, -v58, v57, v56
	v_cmp_ge_f32_e64 s[64:65], 0, v59
	v_add_u32_e32 v59, 1, v57
	s_nop 0
	v_cndmask_b32_e64 v58, v57, v58, s[64:65]
	v_fma_f32 v57, -v59, v57, v56
	v_cmp_lt_f32_e64 s[64:65], 0, v57
	s_nop 1
	v_cndmask_b32_e64 v57, v58, v59, s[64:65]
	v_mul_f32_e32 v58, 0x37800000, v57
	v_cndmask_b32_e32 v57, v57, v58, vcc
	v_cmp_class_f32_e32 vcc, v56, v225
	s_nop 1
	v_cndmask_b32_e32 v56, v57, v56, vcc
	v_div_scale_f32 v57, s[28:29], v56, v56, 1.0
	v_rcp_f32_e32 v58, v57
	s_nop 0
	v_fma_f32 v59, -v57, v58, 1.0
	v_fmac_f32_e32 v58, v59, v58
	v_div_scale_f32 v59, vcc, 1.0, v56, 1.0
	v_mul_f32_e32 v60, v59, v58
	v_fma_f32 v61, -v57, v60, v59
	v_fmac_f32_e32 v60, v61, v58
	v_fma_f32 v57, -v57, v60, v59
	v_div_fmas_f32 v57, v57, v58, v60
	v_div_fixup_f32 v56, v57, v56, 1.0
	v_mul_f32_e32 v52, v52, v56
	v_mul_f32_e32 v52, v36, v52
	v_lshlrev_b32_e32 v57, 16, v132
	v_mul_f32_e32 v53, v53, v56
	v_mul_f32_e32 v52, v52, v57
	v_mul_f32_e32 v53, v37, v53
	v_and_b32_e32 v57, 0xffff0000, v132
	v_mul_f32_e32 v54, v54, v56
	v_mul_f32_e32 v53, v53, v57
	v_mul_f32_e32 v54, v38, v54
	v_lshlrev_b32_e32 v57, 16, v133
	v_mul_f32_e32 v55, v55, v56
	v_mul_f32_e32 v54, v54, v57
	v_mul_f32_e32 v55, v39, v55
	v_and_b32_e32 v57, 0xffff0000, v133
	v_cvt_pk_bf16_f32 v52, v52, v53
	v_mul_f32_e32 v48, v48, v56
	v_mul_f32_e32 v55, v55, v57
	v_cvt_pk_bf16_f32 v53, v54, v55
	ds_write_b64 v202, v[52:53] offset:16896
	v_mul_f32_e32 v48, v32, v48
	v_lshlrev_b32_e32 v52, 16, v130
	v_mul_f32_e32 v49, v49, v56
	v_mul_f32_e32 v48, v48, v52
	v_mul_f32_e32 v49, v33, v49
	v_and_b32_e32 v52, 0xffff0000, v130
	v_mul_f32_e32 v50, v50, v56
	v_mul_f32_e32 v49, v49, v52
	v_mul_f32_e32 v50, v34, v50
	v_lshlrev_b32_e32 v52, 16, v131
	v_mul_f32_e32 v51, v51, v56
	v_mul_f32_e32 v50, v50, v52
	v_mul_f32_e32 v51, v35, v51
	v_and_b32_e32 v52, 0xffff0000, v131
	v_mul_f32_e32 v51, v51, v52
	v_cvt_pk_bf16_f32 v48, v48, v49
	v_cvt_pk_bf16_f32 v49, v50, v51
	ds_write_b64 v202, v[48:49] offset:16928
	ds_read2st64_b32 v[48:49], v193 offset0:156 offset1:157
	s_waitcnt lgkmcnt(0)
	v_add_f32_e32 v48, 0, v48
	v_add_f32_e32 v50, v48, v49
	ds_read2st64_b32 v[48:49], v193 offset0:158 offset1:159
	s_waitcnt lgkmcnt(0)
	v_add_f32_e32 v48, v50, v48
	v_add_f32_e32 v50, v48, v49
	ds_read2st64_b32 v[48:49], v193 offset0:160 offset1:161
	s_waitcnt lgkmcnt(0)
	v_add_f32_e32 v48, v50, v48
	v_add_f32_e32 v50, v48, v49
	ds_read2st64_b32 v[48:49], v193 offset0:162 offset1:163
	s_waitcnt lgkmcnt(0)
	v_add_f32_e32 v48, v50, v48
	v_add_f32_e32 v48, v48, v49
	v_fmamk_f32 v48, v48, 0x3b800000, v226
	v_cmp_gt_f32_e32 vcc, s83, v48
	v_mul_f32_e32 v49, 0x4f800000, v48
	s_nop 0
	v_cndmask_b32_e32 v48, v48, v49, vcc
	v_sqrt_f32_e32 v49, v48
	s_nop 0
	v_add_u32_e32 v50, -1, v49
	v_fma_f32 v51, -v50, v49, v48
	v_cmp_ge_f32_e64 s[64:65], 0, v51
	v_add_u32_e32 v51, 1, v49
	s_nop 0
	v_cndmask_b32_e64 v50, v49, v50, s[64:65]
	v_fma_f32 v49, -v51, v49, v48
	v_cmp_lt_f32_e64 s[64:65], 0, v49
	s_nop 1
	v_cndmask_b32_e64 v49, v50, v51, s[64:65]
	v_mul_f32_e32 v50, 0x37800000, v49
	v_cndmask_b32_e32 v49, v49, v50, vcc
	v_cmp_class_f32_e32 vcc, v48, v225
	s_nop 1
	v_cndmask_b32_e32 v48, v49, v48, vcc
	v_div_scale_f32 v49, s[28:29], v48, v48, 1.0
	v_rcp_f32_e32 v50, v49
	s_nop 0
	v_fma_f32 v51, -v49, v50, 1.0
	v_fmac_f32_e32 v50, v51, v50
	v_div_scale_f32 v51, vcc, 1.0, v48, 1.0
	v_mul_f32_e32 v52, v51, v50
	v_fma_f32 v53, -v49, v52, v51
	v_fmac_f32_e32 v52, v53, v50
	v_fma_f32 v49, -v49, v52, v51
	v_div_fmas_f32 v49, v49, v50, v52
	v_div_fixup_f32 v48, v49, v48, 1.0
	v_mul_f32_e32 v44, v44, v48
	v_mul_f32_e32 v36, v36, v44
	v_lshlrev_b32_e32 v44, 16, v128
	v_mul_f32_e32 v36, v36, v44
	v_mul_f32_e32 v44, v45, v48
	v_mul_f32_e32 v37, v37, v44
	v_and_b32_e32 v44, 0xffff0000, v128
	v_mul_f32_e32 v37, v37, v44
	v_mul_f32_e32 v44, v46, v48
	v_mul_f32_e32 v38, v38, v44
	v_lshlrev_b32_e32 v44, 16, v129
	v_mul_f32_e32 v38, v38, v44
	v_mul_f32_e32 v44, v47, v48
	v_mul_f32_e32 v39, v39, v44
	v_and_b32_e32 v44, 0xffff0000, v129
	v_cvt_pk_bf16_f32 v36, v36, v37
	v_mul_f32_e32 v39, v39, v44
	v_cvt_pk_bf16_f32 v37, v38, v39
	ds_write_b64 v203, v[36:37]
	v_mul_f32_e32 v36, v40, v48
	v_mul_f32_e32 v32, v32, v36
	v_lshlrev_b32_e32 v36, 16, v126
	v_mul_f32_e32 v32, v32, v36
	v_mul_f32_e32 v36, v41, v48
	v_mul_f32_e32 v33, v33, v36
	v_and_b32_e32 v36, 0xffff0000, v126
	v_mul_f32_e32 v33, v33, v36
	v_mul_f32_e32 v36, v42, v48
	v_mul_f32_e32 v34, v34, v36
	v_lshlrev_b32_e32 v36, 16, v127
	v_mul_f32_e32 v34, v34, v36
	v_mul_f32_e32 v36, v43, v48
	v_mul_f32_e32 v35, v35, v36
	v_and_b32_e32 v36, 0xffff0000, v127
	v_mul_f32_e32 v35, v35, v36
	v_cvt_pk_bf16_f32 v32, v32, v33
	v_cvt_pk_bf16_f32 v33, v34, v35
	ds_write_b64 v203, v[32:33] offset:32
	s_waitcnt lgkmcnt(0)
	s_barrier
	s_and_saveexec_b64 s[64:65], s[62:63]
	s_cbranch_execz .LBB0_807
	v_mov_b32_e32 v125, v143
	v_lshlrev_b64 v[32:33], 11, v[124:125]
	v_lshl_add_u64 v[36:37], v[116:117], 0, v[32:33]
	ds_read_b128 v[32:35], v75
	s_waitcnt lgkmcnt(0)
	global_store_dwordx4 v[36:37], v[32:35], off sc1
	s_nop 1
	s_or_b64 exec, exec, s[64:65]
	s_and_saveexec_b64 s[62:63], s[60:61]
	s_cbranch_execnz .LBB0_808
